# side CUs' state-row copy loop: two rows per iteration (12 loads in flight instead of 6)
# baseline (speedup 1.0000x reference)
; #define GAS __attribute__((address_space(1)))
; __device__ __forceinline__ void states_copy_rows(Frame& F, int gw, int NGW) {
;     constexpr int KP_ = PSTATE - DS, KC_ = CSTATE - DS, R_P = DB * KP_, R_C = DB * KC_;
;     const unsigned ln = (unsigned)F.lane;
;     for (int i = gw; i < R_P + R_C; i += NGW) {
;         const float* sf; float* dst;
;         if (i < R_P) { const int b = i / KP_, j = i % KP_; sf = F.in[5] + (size_t)(b * PSTATE + j + DS) * DPOOL; dst = F.out + O_PSS + (size_t)(b * PSTATE + j) * DPOOL; }
;         else { const int r = i - R_P, b = r / KC_, j = r % KC_; sf = F.in[6] + (size_t)(b * CSTATE + j + DS) * DCONV; dst = F.out + O_CSS + (size_t)(b * CSTATE + j) * DCONV; }
;         f32x4 v[6];
; #pragma unroll
;         for (int k = 0; k < 6; ++k) v[k] = ldg<f32x4>(sf, (256u * k + 4u * ln) * 4u);
; #pragma unroll
;         for (int k = 0; k < 6; ++k) *(GAS f32x4*)((char*)dst + (256u * k + 4u * ln) * 4u) = v[k];
;     }
.LBB0_350:
.LBB0_351:
	s_cmpk_gt_i32 s12, 0x57f
	s_cbranch_scc0 .Lsc_pB0
	s_add_i32 s8, s12, 0xfa80
	s_and_b32 s9, s8, 0xffff
	s_mulk_i32 s9, 0x4ec5
	s_lshr_b32 s9, s9, 19
	s_mul_i32 s10, s9, 26
	s_sub_i32 s8, s8, s10
	s_mul_i32 s9, s9, 30
	s_and_b32 s8, s8, 0xffff
	s_add_i32 s8, s9, s8
	s_mulk_i32 s8, 0x1800
	s_add_u32 s9, s6, s8
	s_addc_u32 s11, s7, 0
	s_add_u32 s10, s9, 0x6000
	s_addc_u32 s11, s11, 0
	s_add_u32 s8, s13, s8
	s_addc_u32 s9, s18, 0
	s_branch .Lsc_dd0
.Lsc_pB0:
	s_mul_hi_i32 s8, s12, 0x2e8ba2e9
	s_lshr_b32 s9, s8, 31
	s_lshr_b32 s8, s8, 1
	s_add_i32 s8, s8, s9
	s_lshl_b32 s8, s8, 2
	s_add_i32 s8, s12, s8
	s_mul_i32 s16, s8, 0x1800
	s_add_i32 s9, s8, 4
	s_add_i32 s10, s16, 0x6000
	s_mul_hi_i32 s9, s9, 0x1800
	s_add_u32 s10, s4, s10
	s_addc_u32 s11, s5, s9
	s_mul_hi_i32 s9, s8, 0x1800
	s_add_u32 s8, s19, s16
	s_addc_u32 s9, s20, s9
.Lsc_dd0:
	v_lshl_add_u64 v[76:77], s[10:11], 0, v[2:3]
	v_lshl_add_u64 v[78:79], s[10:11], 0, v[4:5]
	v_lshl_add_u64 v[80:81], s[10:11], 0, v[6:7]
	global_load_dwordx4 v[8:11], v[76:77], off
	global_load_dwordx4 v[12:15], v[76:77], off offset:1024
	global_load_dwordx4 v[16:19], v[76:77], off offset:2048
	global_load_dwordx4 v[20:23], v[76:77], off offset:3072
	global_load_dwordx4 v[24:27], v[78:79], off
	global_load_dwordx4 v[28:31], v[80:81], off
	v_lshl_add_u64 v[32:33], s[8:9], 0, v[2:3]
	v_lshl_add_u64 v[34:35], s[8:9], 0, v[4:5]
	v_lshl_add_u64 v[36:37], s[8:9], 0, v[6:7]
	s_add_i32 s99, s12, 0x100
	s_cmpk_gt_i32 s99, 0x127f
	s_cbranch_scc1 .Lsc_single
	s_cmpk_gt_i32 s99, 0x57f
	s_cbranch_scc0 .Lsc_pB1
	s_add_i32 s8, s99, 0xfa80
	s_and_b32 s9, s8, 0xffff
	s_mulk_i32 s9, 0x4ec5
	s_lshr_b32 s9, s9, 19
	s_mul_i32 s10, s9, 26
	s_sub_i32 s8, s8, s10
	s_mul_i32 s9, s9, 30
	s_and_b32 s8, s8, 0xffff
	s_add_i32 s8, s9, s8
	s_mulk_i32 s8, 0x1800
	s_add_u32 s9, s6, s8
	s_addc_u32 s11, s7, 0
	s_add_u32 s10, s9, 0x6000
	s_addc_u32 s11, s11, 0
	s_add_u32 s8, s13, s8
	s_addc_u32 s9, s18, 0
	s_branch .Lsc_dd1
.Lsc_pB1:
	s_mul_hi_i32 s8, s99, 0x2e8ba2e9
	s_lshr_b32 s9, s8, 31
	s_lshr_b32 s8, s8, 1
	s_add_i32 s8, s8, s9
	s_lshl_b32 s8, s8, 2
	s_add_i32 s8, s99, s8
	s_mul_i32 s16, s8, 0x1800
	s_add_i32 s9, s8, 4
	s_add_i32 s10, s16, 0x6000
	s_mul_hi_i32 s9, s9, 0x1800
	s_add_u32 s10, s4, s10
	s_addc_u32 s11, s5, s9
	s_mul_hi_i32 s9, s8, 0x1800
	s_add_u32 s8, s19, s16
	s_addc_u32 s9, s20, s9
.Lsc_dd1:
	v_lshl_add_u64 v[82:83], s[10:11], 0, v[2:3]
	v_lshl_add_u64 v[84:85], s[10:11], 0, v[4:5]
	v_lshl_add_u64 v[86:87], s[10:11], 0, v[6:7]
	global_load_dwordx4 v[40:43], v[82:83], off
	global_load_dwordx4 v[44:47], v[82:83], off offset:1024
	global_load_dwordx4 v[48:51], v[82:83], off offset:2048
	global_load_dwordx4 v[52:55], v[82:83], off offset:3072
	global_load_dwordx4 v[56:59], v[84:85], off
	global_load_dwordx4 v[60:63], v[86:87], off
	v_lshl_add_u64 v[64:65], s[8:9], 0, v[2:3]
	v_lshl_add_u64 v[66:67], s[8:9], 0, v[4:5]
	v_lshl_add_u64 v[68:69], s[8:9], 0, v[6:7]
	s_waitcnt vmcnt(6)
	global_store_dwordx4 v[32:33], v[8:11], off
	global_store_dwordx4 v[32:33], v[12:15], off offset:1024
	global_store_dwordx4 v[32:33], v[16:19], off offset:2048
	global_store_dwordx4 v[32:33], v[20:23], off offset:3072
	global_store_dwordx4 v[34:35], v[24:27], off
	global_store_dwordx4 v[36:37], v[28:31], off
	s_waitcnt vmcnt(6)
	global_store_dwordx4 v[64:65], v[40:43], off
	global_store_dwordx4 v[64:65], v[44:47], off offset:1024
	global_store_dwordx4 v[64:65], v[48:51], off offset:2048
	global_store_dwordx4 v[64:65], v[52:55], off offset:3072
	global_store_dwordx4 v[66:67], v[56:59], off
	global_store_dwordx4 v[68:69], v[60:63], off
	s_add_i32 s12, s12, 0x200
	s_cmpk_gt_i32 s12, 0x127f
	s_cbranch_scc0 .LBB0_351
	s_branch .LBB0_355
.Lsc_single:
	s_waitcnt vmcnt(0)
	global_store_dwordx4 v[32:33], v[8:11], off
	global_store_dwordx4 v[32:33], v[12:15], off offset:1024
	global_store_dwordx4 v[32:33], v[16:19], off offset:2048
	global_store_dwordx4 v[32:33], v[20:23], off offset:3072
	global_store_dwordx4 v[34:35], v[24:27], off
	global_store_dwordx4 v[36:37], v[28:31], off
